# P5 stage 3: per 16x32 block all LDS reads (8 transposed X reads + 2 decay rows) issued at block start with one wait, tile class by scalar branch; on top of scalarised conv row loads
# speedup vs baseline: 1.0051x; 1.0051x over previous
.LBB0_856:
	s_lshl_b32 s0, s0, 2
	v_add_u32_e32 v142, s0, v132
	ds_read_b32 v120, v142
	v_add_u32_e32 v140, s0, v133
	v_cndmask_b32_e64 v143, 0, 1, s[56:57]
	v_cndmask_b32_e64 v141, 0, 1, s[18:19]
	s_and_b64 s[0:1], s[36:37], exec
	v_readfirstlane_b32 s0, v141
	v_readfirstlane_b32 s1, v143
	s_cselect_b32 s0, s0, s1
	s_bitcmp1_b32 s0, 0
	v_cndmask_b32_e64 v141, 0, 1, s[62:63]
	v_cndmask_b32_e64 v144, 0, 1, s[60:61]
	v_cndmask_b32_e64 v145, 0, 1, s[74:75]
	v_cndmask_b32_e64 v146, 0, 1, s[68:69]
	v_cndmask_b32_e64 v136, v125, v119, s[36:37]
	v_cndmask_b32_e64 v139, v127, v126, s[36:37]
	v_cndmask_b32_e64 v137, v129, v128, s[36:37]
	v_cndmask_b32_e64 v138, v131, v130, s[36:37]
	v_mov_b32_e32 v240, v136
	v_mov_b32_e32 v241, v139
	v_mov_b32_e32 v242, v137
	v_mov_b32_e32 v243, v138
	s_waitcnt lgkmcnt(0)
	v_mov_b32_e32 v121, v120
	s_cselect_b64 s[20:21], -1, 0
	s_bitcmp0_b32 s0, 0
	v_cndmask_b32_e64 v144, v141, v144, s[36:37]
	v_cndmask_b32_e64 v141, v145, v146, s[36:37]
	s_cbranch_scc1 .LBB0_858
	ds_read_b64_tr_b16 v[208:209], v134 offset:34816
	ds_read_b64_tr_b16 v[210:211], v134 offset:43520
	ds_read_b64_tr_b16 v[212:213], v134 offset:34880
	ds_read_b64_tr_b16 v[214:215], v134 offset:43584
	ds_read_b64_tr_b16 v[216:217], v134 offset:34848
	ds_read_b64_tr_b16 v[218:219], v134 offset:43552
	ds_read_b64_tr_b16 v[220:221], v134 offset:34912
	ds_read_b64_tr_b16 v[222:223], v134 offset:43616
	ds_read_b128 v[244:247], v140
	ds_read_b128 v[248:251], v140 offset:64
	s_waitcnt lgkmcnt(0)
	v_readfirstlane_b32 s100, v144
	s_cmp_lg_u64 s[26:27], 0
	s_cbranch_scc1 .Ls3_0_0d
	s_bitcmp1_b32 s100, 0
	s_cbranch_scc0 .Ls3_0_0x

.Ls3_0_0d:
	v_pk_add_f32 v[244:245], v[240:241], v[244:245]
	v_pk_add_f32 v[246:247], v[242:243], v[246:247]
	s_branch .Ls3_0_0c

.Ls3_0_0j:
	v_readfirstlane_b32 s100, v141
	s_cmp_lg_u64 s[4:5], 0
	s_cbranch_scc1 .Ls3_0_1d
	s_bitcmp1_b32 s100, 0
	s_cbranch_scc0 .Ls3_0_1x
.Ls3_0_1c:
	v_pk_add_f32 v[248:249], v[120:121], v[248:249]
	v_pk_add_f32 v[250:251], v[120:121], v[250:251]
	v_exp_f32_e32 v248, v248
	v_exp_f32_e32 v249, v249
	v_exp_f32_e32 v250, v250
	v_exp_f32_e32 v251, v251
	v_pk_mul_f32 v[156:157], v[52:53], v[248:249]
	v_pk_mul_f32 v[158:159], v[54:55], v[250:251]
	s_branch .Ls3_0_1j
.Ls3_0_1d:
	v_pk_add_f32 v[248:249], v[240:241], v[248:249]
	v_pk_add_f32 v[250:251], v[242:243], v[250:251]
	s_branch .Ls3_0_1c

.Ls3_0_1j:
	v_cvt_pk_bf16_f32 v148, v152, v153
	v_cvt_pk_bf16_f32 v149, v154, v155
	v_cvt_pk_bf16_f32 v150, v156, v157
	v_cvt_pk_bf16_f32 v151, v158, v159
	s_nop 1
	v_mfma_f32_16x16x32_bf16 v[92:95], v[208:211], v[148:151], v[92:95]
	v_mfma_f32_16x16x32_bf16 v[68:71], v[212:215], v[148:151], v[68:71]
	v_mfma_f32_16x16x32_bf16 v[80:83], v[216:219], v[148:151], v[80:83]
	v_mfma_f32_16x16x32_bf16 v[60:63], v[220:223], v[148:151], v[60:63]
.LBB0_858:
	v_cndmask_b32_e64 v145, 0, 1, s[76:77]
	s_and_b64 s[0:1], s[36:37], exec
	v_readfirstlane_b32 s0, v146
	v_readfirstlane_b32 s1, v145
	s_cselect_b32 s0, s0, s1
	s_bitcmp1_b32 s0, 0
	v_cndmask_b32_e64 v146, 0, 1, s[80:81]
	v_cndmask_b32_e64 v147, 0, 1, s[88:89]
	v_cndmask_b32_e64 v148, 0, 1, s[84:85]
	s_cselect_b64 s[22:23], -1, 0
	s_bitcmp0_b32 s0, 0
	v_cndmask_b32_e64 v146, v143, v146, s[36:37]
	v_cndmask_b32_e64 v143, v147, v148, s[36:37]
	s_cbranch_scc1 .LBB0_860
	ds_read_b64_tr_b16 v[208:209], v134 offset:52224
	ds_read_b64_tr_b16 v[210:211], v134 offset:60928
	ds_read_b64_tr_b16 v[212:213], v134 offset:52288
	ds_read_b64_tr_b16 v[214:215], v134 offset:60992
	ds_read_b64_tr_b16 v[216:217], v134 offset:52256
	ds_read_b64_tr_b16 v[218:219], v134 offset:60960
	ds_read_b64_tr_b16 v[220:221], v134 offset:52320
	ds_read_b64_tr_b16 v[222:223], v134 offset:61024
	ds_read_b128 v[244:247], v140 offset:128
	ds_read_b128 v[248:251], v140 offset:192
	s_waitcnt lgkmcnt(0)
	v_readfirstlane_b32 s100, v146
	s_cmp_lg_u64 s[6:7], 0
	s_cbranch_scc1 .Ls3_1_0d
	s_bitcmp1_b32 s100, 0
	s_cbranch_scc0 .Ls3_1_0x

.Ls3_1_0j:
	v_readfirstlane_b32 s100, v143
	s_cmp_lg_u64 s[8:9], 0
	s_cbranch_scc1 .Ls3_1_1d
	s_bitcmp1_b32 s100, 0
	s_cbranch_scc0 .Ls3_1_1x
.Ls3_1_1c:
	v_pk_add_f32 v[248:249], v[120:121], v[248:249]
	v_pk_add_f32 v[250:251], v[120:121], v[250:251]
	v_exp_f32_e32 v248, v248
	v_exp_f32_e32 v249, v249
	v_exp_f32_e32 v250, v250
	v_exp_f32_e32 v251, v251
	v_pk_mul_f32 v[158:159], v[64:65], v[248:249]
	v_pk_mul_f32 v[162:163], v[66:67], v[250:251]
	s_branch .Ls3_1_1j

.Ls3_1_1j:
	v_cvt_pk_bf16_f32 v150, v154, v155
	v_cvt_pk_bf16_f32 v151, v156, v157
	v_cvt_pk_bf16_f32 v152, v158, v159
	v_cvt_pk_bf16_f32 v153, v162, v163
	s_nop 1
	v_mfma_f32_16x16x32_bf16 v[92:95], v[208:211], v[150:153], v[92:95]
	v_mfma_f32_16x16x32_bf16 v[68:71], v[212:215], v[150:153], v[68:71]
	v_mfma_f32_16x16x32_bf16 v[80:83], v[216:219], v[150:153], v[80:83]
	v_mfma_f32_16x16x32_bf16 v[60:63], v[220:223], v[150:153], v[60:63]
.LBB0_860:
	v_cndmask_b32_e64 v147, 0, 1, s[94:95]
	s_and_b64 s[0:1], s[36:37], exec
	v_readfirstlane_b32 s0, v148
	v_readfirstlane_b32 s1, v147
	s_cselect_b32 s0, s0, s1
	s_bitcmp1_b32 s0, 0
	v_cndmask_b32_e64 v148, 0, 1, s[96:97]
	v_cndmask_b32_e64 v150, 0, 1, s[64:65]
	v_cndmask_b32_e64 v149, 0, 1, s[92:93]
	s_cselect_b64 s[24:25], -1, 0
	s_bitcmp0_b32 s0, 0
	v_cndmask_b32_e64 v148, v145, v148, s[36:37]
	v_cndmask_b32_e64 v145, v150, v149, s[36:37]
	s_cbranch_scc1 .LBB0_862
	ds_read_b64_tr_b16 v[208:209], v135 offset:34816
	ds_read_b64_tr_b16 v[210:211], v135 offset:43520
	ds_read_b64_tr_b16 v[212:213], v135 offset:34880
	ds_read_b64_tr_b16 v[214:215], v135 offset:43584
	ds_read_b64_tr_b16 v[216:217], v135 offset:34848
	ds_read_b64_tr_b16 v[218:219], v135 offset:43552
	ds_read_b64_tr_b16 v[220:221], v135 offset:34912
	ds_read_b64_tr_b16 v[222:223], v135 offset:43616
	ds_read_b128 v[244:247], v140 offset:256
	ds_read_b128 v[248:251], v140 offset:320
	s_waitcnt lgkmcnt(0)
	v_readfirstlane_b32 s100, v148
	s_cmp_lg_u64 s[10:11], 0
	s_cbranch_scc1 .Ls3_2_0d
	s_bitcmp1_b32 s100, 0
	s_cbranch_scc0 .Ls3_2_0x

.Ls3_2_0j:
	v_readfirstlane_b32 s100, v145
	s_cmp_lg_u64 s[12:13], 0
	s_cbranch_scc1 .Ls3_2_1d
	s_bitcmp1_b32 s100, 0
	s_cbranch_scc0 .Ls3_2_1x
.Ls3_2_1c:
	v_pk_add_f32 v[248:249], v[120:121], v[248:249]
	v_pk_add_f32 v[250:251], v[120:121], v[250:251]
	v_exp_f32_e32 v248, v248
	v_exp_f32_e32 v249, v249
	v_exp_f32_e32 v250, v250
	v_exp_f32_e32 v251, v251
	v_pk_mul_f32 v[158:159], v[76:77], v[248:249]
	v_pk_mul_f32 v[162:163], v[78:79], v[250:251]
	s_branch .Ls3_2_1j

.LBB0_862:
	v_cndmask_b32_e64 v150, 0, 1, s[42:43]
	s_and_b64 s[0:1], s[36:37], exec
	v_readfirstlane_b32 s0, v149
	v_readfirstlane_b32 s1, v150
	s_cselect_b32 s0, s0, s1
	s_bitcmp1_b32 s0, 0
	v_cndmask_b32_e64 v149, 0, 1, s[58:59]
	v_cndmask_b32_e64 v150, 0, 1, s[90:91]
	v_cndmask_b32_e64 v151, 0, 1, s[66:67]
	s_cselect_b64 s[40:41], -1, 0
	s_bitcmp0_b32 s0, 0
	v_cndmask_b32_e64 v149, v147, v149, s[36:37]
	v_cndmask_b32_e64 v147, v150, v151, s[36:37]
	s_cbranch_scc1 .LBB0_864
	ds_read_b64_tr_b16 v[208:209], v135 offset:52224
	ds_read_b64_tr_b16 v[210:211], v135 offset:60928
	ds_read_b64_tr_b16 v[212:213], v135 offset:52288
	ds_read_b64_tr_b16 v[214:215], v135 offset:60992
	ds_read_b64_tr_b16 v[216:217], v135 offset:52256
	ds_read_b64_tr_b16 v[218:219], v135 offset:60960
	ds_read_b64_tr_b16 v[220:221], v135 offset:52320
	ds_read_b64_tr_b16 v[222:223], v135 offset:61024
	ds_read_b128 v[244:247], v140 offset:384
	ds_read_b128 v[248:251], v140 offset:448
	s_waitcnt lgkmcnt(0)
	v_readfirstlane_b32 s100, v149
	s_cmp_lg_u64 s[14:15], 0
	s_cbranch_scc1 .Ls3_3_0d
	s_bitcmp1_b32 s100, 0
	s_cbranch_scc0 .Ls3_3_0x

.Ls3_3_0j:
	v_readfirstlane_b32 s100, v147
	s_cmp_lg_u64 s[16:17], 0
	s_cbranch_scc1 .Ls3_3_1d
	s_bitcmp1_b32 s100, 0
	s_cbranch_scc0 .Ls3_3_1x
.Ls3_3_1c:
	v_pk_add_f32 v[248:249], v[120:121], v[248:249]
	v_pk_add_f32 v[250:251], v[120:121], v[250:251]
	v_exp_f32_e32 v248, v248
	v_exp_f32_e32 v249, v249
	v_exp_f32_e32 v250, v250
	v_exp_f32_e32 v251, v251
	v_pk_mul_f32 v[152:153], v[88:89], v[248:249]
	v_pk_mul_f32 v[120:121], v[90:91], v[250:251]
	s_branch .Ls3_3_1j

.Ls3_3_1j:
	v_cvt_pk_bf16_f32 v150, v154, v155
	v_cvt_pk_bf16_f32 v151, v156, v157
	v_cvt_pk_bf16_f32 v152, v152, v153
	v_cvt_pk_bf16_f32 v153, v120, v121
	s_nop 1
	v_mfma_f32_16x16x32_bf16 v[92:95], v[208:211], v[150:153], v[92:95]
	v_mfma_f32_16x16x32_bf16 v[68:71], v[212:215], v[150:153], v[68:71]
	v_mfma_f32_16x16x32_bf16 v[80:83], v[216:219], v[150:153], v[80:83]
	v_mfma_f32_16x16x32_bf16 v[60:63], v[220:223], v[150:153], v[60:63]
.LBB0_864:
	ds_read_b32 v120, v142 offset:512
	v_cndmask_b32_e64 v121, 0, 1, s[20:21]
	v_cmp_ne_u32_e64 s[0:1], 1, v121
	s_andn2_b64 vcc, exec, s[20:21]
	s_waitcnt lgkmcnt(0)
	v_mov_b32_e32 v121, v120
	s_cbranch_vccnz .LBB0_866
	ds_read_b64_tr_b16 v[208:209], v134 offset:34944
	ds_read_b64_tr_b16 v[210:211], v134 offset:43648
	ds_read_b64_tr_b16 v[212:213], v134 offset:35008
	ds_read_b64_tr_b16 v[214:215], v134 offset:43712
	ds_read_b64_tr_b16 v[216:217], v134 offset:34976
	ds_read_b64_tr_b16 v[218:219], v134 offset:43680
	ds_read_b64_tr_b16 v[220:221], v134 offset:35040
	ds_read_b64_tr_b16 v[222:223], v134 offset:43744
	ds_read_b128 v[244:247], v140 offset:512
	ds_read_b128 v[248:251], v140 offset:576
	s_waitcnt lgkmcnt(0)
	v_readfirstlane_b32 s100, v144
	s_cmp_lg_u64 s[26:27], 0
	s_cbranch_scc1 .Ls3_4_0d
	s_bitcmp1_b32 s100, 0
	s_cbranch_scc0 .Ls3_4_0x

.Ls3_4_1c:
	v_pk_add_f32 v[248:249], v[120:121], v[248:249]
	v_pk_add_f32 v[250:251], v[120:121], v[250:251]
	v_exp_f32_e32 v248, v248
	v_exp_f32_e32 v249, v249
	v_exp_f32_e32 v250, v250
	v_exp_f32_e32 v251, v251
	v_pk_mul_f32 v[158:159], v[52:53], v[248:249]
	v_pk_mul_f32 v[162:163], v[54:55], v[250:251]
	s_branch .Ls3_4_1j

.Ls3_4_1j:
	v_cvt_pk_bf16_f32 v150, v154, v155
	v_cvt_pk_bf16_f32 v151, v156, v157
	v_cvt_pk_bf16_f32 v152, v158, v159
	v_cvt_pk_bf16_f32 v153, v162, v163
	s_nop 1
	v_mfma_f32_16x16x32_bf16 v[48:51], v[208:211], v[150:153], v[48:51]
	v_mfma_f32_16x16x32_bf16 v[36:39], v[212:215], v[150:153], v[36:39]
	v_mfma_f32_16x16x32_bf16 v[40:43], v[216:219], v[150:153], v[40:43]
	v_mfma_f32_16x16x32_bf16 v[24:27], v[220:223], v[150:153], v[24:27]
.LBB0_866:
	v_cndmask_b32_e64 v150, 0, 1, s[22:23]
	v_cmp_ne_u32_e64 s[20:21], 1, v150
	s_andn2_b64 vcc, exec, s[22:23]
	s_cbranch_vccnz .LBB0_868
	ds_read_b64_tr_b16 v[208:209], v134 offset:52352
	ds_read_b64_tr_b16 v[210:211], v134 offset:61056
	ds_read_b64_tr_b16 v[212:213], v134 offset:52416
	ds_read_b64_tr_b16 v[214:215], v134 offset:61120
	ds_read_b64_tr_b16 v[216:217], v134 offset:52384
	ds_read_b64_tr_b16 v[218:219], v134 offset:61088
	ds_read_b64_tr_b16 v[220:221], v134 offset:52448
	ds_read_b64_tr_b16 v[222:223], v134 offset:61152
	ds_read_b128 v[244:247], v140 offset:640
	ds_read_b128 v[248:251], v140 offset:704
	s_waitcnt lgkmcnt(0)
	v_readfirstlane_b32 s100, v146
	s_cmp_lg_u64 s[6:7], 0
	s_cbranch_scc1 .Ls3_5_0d
	s_bitcmp1_b32 s100, 0
	s_cbranch_scc0 .Ls3_5_0x

.LBB0_868:
	v_cndmask_b32_e64 v150, 0, 1, s[24:25]
	v_cmp_ne_u32_e64 s[22:23], 1, v150
	s_andn2_b64 vcc, exec, s[24:25]
	s_cbranch_vccnz .LBB0_870
	ds_read_b64_tr_b16 v[208:209], v135 offset:34944
	ds_read_b64_tr_b16 v[210:211], v135 offset:43648
	ds_read_b64_tr_b16 v[212:213], v135 offset:35008
	ds_read_b64_tr_b16 v[214:215], v135 offset:43712
	ds_read_b64_tr_b16 v[216:217], v135 offset:34976
	ds_read_b64_tr_b16 v[218:219], v135 offset:43680
	ds_read_b64_tr_b16 v[220:221], v135 offset:35040
	ds_read_b64_tr_b16 v[222:223], v135 offset:43744
	ds_read_b128 v[244:247], v140 offset:768
	ds_read_b128 v[248:251], v140 offset:832
	s_waitcnt lgkmcnt(0)
	v_readfirstlane_b32 s100, v148
	s_cmp_lg_u64 s[10:11], 0
	s_cbranch_scc1 .Ls3_6_0d
	s_bitcmp1_b32 s100, 0
	s_cbranch_scc0 .Ls3_6_0x

.LBB0_870:
	v_cndmask_b32_e64 v150, 0, 1, s[40:41]
	v_cmp_ne_u32_e64 s[24:25], 1, v150
	s_andn2_b64 vcc, exec, s[40:41]
	s_cbranch_vccnz .LBB0_872
	ds_read_b64_tr_b16 v[208:209], v135 offset:52352
	ds_read_b64_tr_b16 v[210:211], v135 offset:61056
	ds_read_b64_tr_b16 v[212:213], v135 offset:52416
	ds_read_b64_tr_b16 v[214:215], v135 offset:61120
	ds_read_b64_tr_b16 v[216:217], v135 offset:52384
	ds_read_b64_tr_b16 v[218:219], v135 offset:61088
	ds_read_b64_tr_b16 v[220:221], v135 offset:52448
	ds_read_b64_tr_b16 v[222:223], v135 offset:61152
	ds_read_b128 v[244:247], v140 offset:896
	ds_read_b128 v[248:251], v140 offset:960
	s_waitcnt lgkmcnt(0)
	v_readfirstlane_b32 s100, v149
	s_cmp_lg_u64 s[14:15], 0
	s_cbranch_scc1 .Ls3_7_0d
	s_bitcmp1_b32 s100, 0
	s_cbranch_scc0 .Ls3_7_0x

.Ls3_7_1j:
	v_cvt_pk_bf16_f32 v150, v154, v155
	v_cvt_pk_bf16_f32 v151, v156, v157
	v_cvt_pk_bf16_f32 v152, v152, v153
	v_cvt_pk_bf16_f32 v153, v120, v121
	s_nop 1
	v_mfma_f32_16x16x32_bf16 v[48:51], v[208:211], v[150:153], v[48:51]
	v_mfma_f32_16x16x32_bf16 v[36:39], v[212:215], v[150:153], v[36:39]
	v_mfma_f32_16x16x32_bf16 v[40:43], v[216:219], v[150:153], v[40:43]
	v_mfma_f32_16x16x32_bf16 v[24:27], v[220:223], v[150:153], v[24:27]
.LBB0_872:
	ds_read_b32 v120, v142 offset:1024
	s_and_b64 vcc, exec, s[0:1]
	s_waitcnt lgkmcnt(0)
	v_mov_b32_e32 v121, v120
	s_cbranch_vccnz .LBB0_874
	ds_read_b64_tr_b16 v[208:209], v134 offset:35072
	ds_read_b64_tr_b16 v[210:211], v134 offset:43776
	ds_read_b64_tr_b16 v[212:213], v134 offset:35136
	ds_read_b64_tr_b16 v[214:215], v134 offset:43840
	ds_read_b64_tr_b16 v[216:217], v134 offset:35104
	ds_read_b64_tr_b16 v[218:219], v134 offset:43808
	ds_read_b64_tr_b16 v[220:221], v134 offset:35168
	ds_read_b64_tr_b16 v[222:223], v134 offset:43872
	ds_read_b128 v[244:247], v140 offset:1024
	ds_read_b128 v[248:251], v140 offset:1088
	s_waitcnt lgkmcnt(0)
	v_readfirstlane_b32 s100, v144
	s_cmp_lg_u64 s[26:27], 0
	s_cbranch_scc1 .Ls3_8_0d
	s_bitcmp1_b32 s100, 0
	s_cbranch_scc0 .Ls3_8_0x

.Ls3_8_1j:
	v_cvt_pk_bf16_f32 v150, v154, v155
	v_cvt_pk_bf16_f32 v151, v156, v157
	v_cvt_pk_bf16_f32 v152, v158, v159
	v_cvt_pk_bf16_f32 v153, v162, v163
	s_nop 1
	v_mfma_f32_16x16x32_bf16 v[32:35], v[208:211], v[150:153], v[32:35]
	v_mfma_f32_16x16x32_bf16 v[20:23], v[212:215], v[150:153], v[20:23]
	v_mfma_f32_16x16x32_bf16 v[28:31], v[216:219], v[150:153], v[28:31]
	v_mfma_f32_16x16x32_bf16 v[16:19], v[220:223], v[150:153], v[16:19]
.LBB0_874:
	s_and_b64 vcc, exec, s[20:21]
	s_cbranch_vccnz .LBB0_876
	ds_read_b64_tr_b16 v[208:209], v134 offset:52480
	ds_read_b64_tr_b16 v[210:211], v134 offset:61184
	ds_read_b64_tr_b16 v[212:213], v134 offset:52544
	ds_read_b64_tr_b16 v[214:215], v134 offset:61248
	ds_read_b64_tr_b16 v[216:217], v134 offset:52512
	ds_read_b64_tr_b16 v[218:219], v134 offset:61216
	ds_read_b64_tr_b16 v[220:221], v134 offset:52576
	ds_read_b64_tr_b16 v[222:223], v134 offset:61280
	ds_read_b128 v[244:247], v140 offset:1152
	ds_read_b128 v[248:251], v140 offset:1216
	s_waitcnt lgkmcnt(0)
	v_readfirstlane_b32 s100, v146
	s_cmp_lg_u64 s[6:7], 0
	s_cbranch_scc1 .Ls3_9_0d
	s_bitcmp1_b32 s100, 0
	s_cbranch_scc0 .Ls3_9_0x

.LBB0_876:
	s_and_b64 vcc, exec, s[22:23]
	s_cbranch_vccnz .LBB0_878
	ds_read_b64_tr_b16 v[208:209], v135 offset:35072
	ds_read_b64_tr_b16 v[210:211], v135 offset:43776
	ds_read_b64_tr_b16 v[212:213], v135 offset:35136
	ds_read_b64_tr_b16 v[214:215], v135 offset:43840
	ds_read_b64_tr_b16 v[216:217], v135 offset:35104
	ds_read_b64_tr_b16 v[218:219], v135 offset:43808
	ds_read_b64_tr_b16 v[220:221], v135 offset:35168
	ds_read_b64_tr_b16 v[222:223], v135 offset:43872
	ds_read_b128 v[244:247], v140 offset:1280
	ds_read_b128 v[248:251], v140 offset:1344
	s_waitcnt lgkmcnt(0)
	v_readfirstlane_b32 s100, v148
	s_cmp_lg_u64 s[10:11], 0
	s_cbranch_scc1 .Ls3_10_0d
	s_bitcmp1_b32 s100, 0
	s_cbranch_scc0 .Ls3_10_0x

.LBB0_878:
	s_and_b64 vcc, exec, s[24:25]
	s_cbranch_vccnz .LBB0_880
	ds_read_b64_tr_b16 v[208:209], v135 offset:52480
	ds_read_b64_tr_b16 v[210:211], v135 offset:61184
	ds_read_b64_tr_b16 v[212:213], v135 offset:52544
	ds_read_b64_tr_b16 v[214:215], v135 offset:61248
	ds_read_b64_tr_b16 v[216:217], v135 offset:52512
	ds_read_b64_tr_b16 v[218:219], v135 offset:61216
	ds_read_b64_tr_b16 v[220:221], v135 offset:52576
	ds_read_b64_tr_b16 v[222:223], v135 offset:61280
	ds_read_b128 v[244:247], v140 offset:1408
	ds_read_b128 v[248:251], v140 offset:1472
	s_waitcnt lgkmcnt(0)
	v_readfirstlane_b32 s100, v149
	s_cmp_lg_u64 s[14:15], 0
	s_cbranch_scc1 .Ls3_11_0d
	s_bitcmp1_b32 s100, 0
	s_cbranch_scc0 .Ls3_11_0x

.Ls3_11_1j:
	v_cvt_pk_bf16_f32 v150, v154, v155
	v_cvt_pk_bf16_f32 v151, v156, v157
	v_cvt_pk_bf16_f32 v152, v152, v153
	v_cvt_pk_bf16_f32 v153, v120, v121
	s_nop 1
	v_mfma_f32_16x16x32_bf16 v[32:35], v[208:211], v[150:153], v[32:35]
	v_mfma_f32_16x16x32_bf16 v[20:23], v[212:215], v[150:153], v[20:23]
	v_mfma_f32_16x16x32_bf16 v[28:31], v[216:219], v[150:153], v[28:31]
	v_mfma_f32_16x16x32_bf16 v[16:19], v[220:223], v[150:153], v[16:19]
.LBB0_880:
	ds_read_b32 v120, v142 offset:1536
	s_and_b64 vcc, exec, s[0:1]
	s_waitcnt lgkmcnt(0)
	v_mov_b32_e32 v121, v120
	s_cbranch_vccnz .LBB0_882
	ds_read_b64_tr_b16 v[208:209], v134 offset:35200
	ds_read_b64_tr_b16 v[210:211], v134 offset:43904
	ds_read_b64_tr_b16 v[212:213], v134 offset:35264
	ds_read_b64_tr_b16 v[214:215], v134 offset:43968
	ds_read_b64_tr_b16 v[216:217], v134 offset:35232
	ds_read_b64_tr_b16 v[218:219], v134 offset:43936
	ds_read_b64_tr_b16 v[220:221], v134 offset:35296
	ds_read_b64_tr_b16 v[222:223], v134 offset:44000
	ds_read_b128 v[244:247], v140 offset:1536
	ds_read_b128 v[248:251], v140 offset:1600
	s_waitcnt lgkmcnt(0)
	v_readfirstlane_b32 s100, v144
	s_cmp_lg_u64 s[26:27], 0
	s_cbranch_scc1 .Ls3_12_0d
	s_bitcmp1_b32 s100, 0
	s_cbranch_scc0 .Ls3_12_0x

.Ls3_12_1j:
	v_cvt_pk_bf16_f32 v150, v154, v155
	v_cvt_pk_bf16_f32 v151, v156, v157
	v_cvt_pk_bf16_f32 v152, v158, v159
	v_cvt_pk_bf16_f32 v153, v162, v163
	s_nop 1
	v_mfma_f32_16x16x32_bf16 v[12:15], v[208:211], v[150:153], v[12:15]
	v_mfma_f32_16x16x32_bf16 v[4:7], v[212:215], v[150:153], v[4:7]
	v_mfma_f32_16x16x32_bf16 v[8:11], v[216:219], v[150:153], v[8:11]
	v_mfma_f32_16x16x32_bf16 v[0:3], v[220:223], v[150:153], v[0:3]
.LBB0_882:
	s_and_b64 vcc, exec, s[20:21]
	s_cbranch_vccnz .LBB0_884
	ds_read_b64_tr_b16 v[208:209], v134 offset:52608
	ds_read_b64_tr_b16 v[210:211], v134 offset:61312
	ds_read_b64_tr_b16 v[212:213], v134 offset:52672
	ds_read_b64_tr_b16 v[214:215], v134 offset:61376
	ds_read_b64_tr_b16 v[216:217], v134 offset:52640
	ds_read_b64_tr_b16 v[218:219], v134 offset:61344
	ds_read_b64_tr_b16 v[220:221], v134 offset:52704
	ds_read_b64_tr_b16 v[222:223], v134 offset:61408
	ds_read_b128 v[244:247], v140 offset:1664
	ds_read_b128 v[248:251], v140 offset:1728
	s_waitcnt lgkmcnt(0)
	v_readfirstlane_b32 s100, v146
	s_cmp_lg_u64 s[6:7], 0
	s_cbranch_scc1 .Ls3_13_0d
	s_bitcmp1_b32 s100, 0
	s_cbranch_scc0 .Ls3_13_0x

.Ls3_13_1c:
	v_pk_add_f32 v[248:249], v[120:121], v[248:249]
	v_pk_add_f32 v[250:251], v[120:121], v[250:251]
	v_exp_f32_e32 v248, v248
	v_exp_f32_e32 v249, v249
	v_exp_f32_e32 v250, v250
	v_exp_f32_e32 v251, v251
	v_pk_mul_f32 v[142:143], v[64:65], v[248:249]
	v_pk_mul_f32 v[158:159], v[66:67], v[250:251]
	s_branch .Ls3_13_1j

.Ls3_13_1j:
	v_cvt_pk_bf16_f32 v150, v154, v155
	v_cvt_pk_bf16_f32 v151, v156, v157
	v_cvt_pk_bf16_f32 v152, v142, v143
	v_cvt_pk_bf16_f32 v153, v158, v159
	s_nop 1
	v_mfma_f32_16x16x32_bf16 v[12:15], v[208:211], v[150:153], v[12:15]
	v_mfma_f32_16x16x32_bf16 v[4:7], v[212:215], v[150:153], v[4:7]
	v_mfma_f32_16x16x32_bf16 v[8:11], v[216:219], v[150:153], v[8:11]
	v_mfma_f32_16x16x32_bf16 v[0:3], v[220:223], v[150:153], v[0:3]
.LBB0_884:
	s_and_b64 vcc, exec, s[22:23]
	s_cbranch_vccnz .LBB0_886
	ds_read_b64_tr_b16 v[208:209], v135 offset:35200
	ds_read_b64_tr_b16 v[210:211], v135 offset:43904
	ds_read_b64_tr_b16 v[212:213], v135 offset:35264
	ds_read_b64_tr_b16 v[214:215], v135 offset:43968
	ds_read_b64_tr_b16 v[216:217], v135 offset:35232
	ds_read_b64_tr_b16 v[218:219], v135 offset:43936
	ds_read_b64_tr_b16 v[220:221], v135 offset:35296
	ds_read_b64_tr_b16 v[222:223], v135 offset:44000
	ds_read_b128 v[244:247], v140 offset:1792
	ds_read_b128 v[248:251], v140 offset:1856
	s_waitcnt lgkmcnt(0)
	v_readfirstlane_b32 s100, v148
	s_cmp_lg_u64 s[10:11], 0
	s_cbranch_scc1 .Ls3_14_0d
	s_bitcmp1_b32 s100, 0
	s_cbranch_scc0 .Ls3_14_0x

.Ls3_14_1c:
	v_pk_add_f32 v[248:249], v[120:121], v[248:249]
	v_pk_add_f32 v[250:251], v[120:121], v[250:251]
	v_exp_f32_e32 v248, v248
	v_exp_f32_e32 v249, v249
	v_exp_f32_e32 v250, v250
	v_exp_f32_e32 v251, v251
	v_pk_mul_f32 v[154:155], v[76:77], v[248:249]
	v_pk_mul_f32 v[156:157], v[78:79], v[250:251]
	s_branch .Ls3_14_1j

.Ls3_14_1j:
	v_cvt_pk_bf16_f32 v142, v152, v153
	v_cvt_pk_bf16_f32 v143, v150, v151
	v_cvt_pk_bf16_f32 v144, v154, v155
	v_cvt_pk_bf16_f32 v145, v156, v157
	s_nop 1
	v_mfma_f32_16x16x32_bf16 v[12:15], v[208:211], v[142:145], v[12:15]
	v_mfma_f32_16x16x32_bf16 v[4:7], v[212:215], v[142:145], v[4:7]
	v_mfma_f32_16x16x32_bf16 v[8:11], v[216:219], v[142:145], v[8:11]
	v_mfma_f32_16x16x32_bf16 v[0:3], v[220:223], v[142:145], v[0:3]
.LBB0_886:
	s_and_b64 vcc, exec, s[24:25]
	s_cbranch_vccnz .LBB0_855
	ds_read_b64_tr_b16 v[208:209], v135 offset:52608
	ds_read_b64_tr_b16 v[210:211], v135 offset:61312
	ds_read_b64_tr_b16 v[212:213], v135 offset:52672
	ds_read_b64_tr_b16 v[214:215], v135 offset:61376
	ds_read_b64_tr_b16 v[216:217], v135 offset:52640
	ds_read_b64_tr_b16 v[218:219], v135 offset:61344
	ds_read_b64_tr_b16 v[220:221], v135 offset:52704
	ds_read_b64_tr_b16 v[222:223], v135 offset:61408
	ds_read_b128 v[244:247], v140 offset:1920
	ds_read_b128 v[248:251], v140 offset:1984
	s_waitcnt lgkmcnt(0)
	v_readfirstlane_b32 s100, v149
	s_cmp_lg_u64 s[14:15], 0
	s_cbranch_scc1 .Ls3_15_0d
	s_bitcmp1_b32 s100, 0
	s_cbranch_scc0 .Ls3_15_0x

.Ls3_15_1c:
	v_pk_add_f32 v[248:249], v[120:121], v[248:249]
	v_pk_add_f32 v[250:251], v[120:121], v[250:251]
	v_exp_f32_e32 v248, v248
	v_exp_f32_e32 v249, v249
	v_exp_f32_e32 v250, v250
	v_exp_f32_e32 v251, v251
	v_pk_mul_f32 v[138:139], v[88:89], v[248:249]
	v_pk_mul_f32 v[120:121], v[90:91], v[250:251]
	s_branch .Ls3_15_1j

.Ls3_15_1j:
	v_cvt_pk_bf16_f32 v136, v148, v149
	v_cvt_pk_bf16_f32 v137, v144, v145
	v_cvt_pk_bf16_f32 v138, v138, v139
	v_cvt_pk_bf16_f32 v139, v120, v121
	s_nop 1
	v_mfma_f32_16x16x32_bf16 v[12:15], v[208:211], v[136:139], v[12:15]
	v_mfma_f32_16x16x32_bf16 v[4:7], v[212:215], v[136:139], v[4:7]
	v_mfma_f32_16x16x32_bf16 v[8:11], v[216:219], v[136:139], v[8:11]
	v_mfma_f32_16x16x32_bf16 v[0:3], v[220:223], v[136:139], v[0:3]
	s_branch .LBB0_855
